# prologue keeps only layer-0 IN/UQ/KV/A/O weight transposes; the rest run in idle WGs of P1/P2/P4/P5/P6 tail rounds
# baseline (speedup 1.0000x reference)
; DEVI const float* IN(int i) { return *(const float* const __attribute__((address_space(4)))*)(kargs() + 8 * i); }
; DEVI void prologue(int wv, LAS unsigned char* lds) {
;     ...
;     for (int it = gw; it < 2 * I_L; it += NGW) {
;         const int l = it / I_L; int r = it % I_L;
;         unsigned char* wl = ws + O_W + (size_t)l * W_LAYER;
;         if (r < I_IN) { const int kb = r / 101, nb = r % 101, n0 = nb * 32;
;             const int d0 = n0 < 384 ? n0 : n0 < 640 ? 512 + (n0 - 384) : n0 < 672 ? 384 + (n0 - 640) : n0 < 1184 ? 768 + (n0 - 672) : n0 < 2208 ? 1280 + (n0 - 1184) : 2304 + (n0 - 2208);
;             tr_item(IN(6) + (size_t)l * 1024 * 3232, 3232, 1024, IN(5) + l * 1024, (bf16_t*)(wl + W_IN), d0, scr, kb * 64, n0, lane); continue; }
.LBB0_23:
	s_or_b64 exec, exec, s[2:3]
	s_mov_b32 s16, s85
	s_mov_b32 s18, s95
	s_mov_b64 s[6:7], s[0:1]
	s_waitcnt lgkmcnt(0)
	s_barrier
	v_mbcnt_lo_u32_b32 v64, -1, 0
	v_mbcnt_hi_u32_b32 v64, -1, v64
	v_lshl_or_b32 v64, s33, 6, v64
	s_load_dwordx2 s[20:21], s[6:7], 0xb0
	v_readfirstlane_b32 s2, v64
	s_ashr_i32 s2, s2, 6
	s_lshl_b32 s3, s18, 3
	v_and_b32_e32 v34, 63, v64
	s_add_i32 s4, s3, s2
	s_lshl_b32 s14, s16, 3
	s_ashr_i32 s17, s16, 31
	v_ashrrev_i32_e32 v65, 31, v64
	s_movk_i32 s52, 0x35bf
	s_cmp_eq_u32 s16, 0x100
	s_cselect_b32 s52, 0xadf, s52
	s_cmp_gt_i32 s4, s52
	v_lshlrev_b32_e32 v66, 3, v34
	s_cbranch_scc1 .LBB0_328
	v_lshrrev_b32_e32 v0, 5, v34
	s_movk_i32 s3, 0x84
	v_mov_b32_e32 v1, 0x108
	v_mad_u32_u24 v13, v0, s3, v1
	v_mov_b32_e32 v1, 0x210
	v_mad_u32_u24 v15, v0, s3, v1
	v_mov_b32_e32 v1, 0x318
	v_mad_u32_u24 v17, v0, s3, v1
	v_mov_b32_e32 v1, 0x420
	v_mad_u32_u24 v19, v0, s3, v1
	v_mov_b32_e32 v1, 0x528
	v_mad_u32_u24 v21, v0, s3, v1
	v_mov_b32_e32 v1, 0x630
	v_mad_u32_u24 v23, v0, s3, v1
	v_mov_b32_e32 v1, 0x738
	v_mad_u32_u24 v25, v0, s3, v1
	v_mov_b32_e32 v1, 0x840
	v_mad_u32_u24 v27, v0, s3, v1
	v_mov_b32_e32 v1, 0x948
	v_mad_u32_u24 v29, v0, s3, v1
	v_mov_b32_e32 v1, 0xa50
	v_mad_u32_u24 v31, v0, s3, v1
	v_mov_b32_e32 v1, 0xb58
	v_mad_u32_u24 v33, v0, s3, v1
	v_mov_b32_e32 v1, 0xc60
	v_mad_u32_u24 v36, v0, s3, v1
	v_mov_b32_e32 v1, 0xd68
	v_mad_u32_u24 v38, v0, s3, v1
	v_mov_b32_e32 v1, 0xe70
	v_mad_u32_u24 v40, v0, s3, v1
	v_mov_b32_e32 v1, 0xf78
	v_mad_u32_u24 v42, v0, s3, v1
	v_mov_b32_e32 v1, 0x1080
	v_mad_u32_u24 v44, v0, s3, v1
	v_mov_b32_e32 v1, 0x1188
	v_mad_u32_u24 v46, v0, s3, v1
	v_mov_b32_e32 v1, 0x1290
	v_mad_u32_u24 v48, v0, s3, v1
	v_mov_b32_e32 v1, 0x1398
	v_mad_u32_u24 v50, v0, s3, v1
	v_mov_b32_e32 v1, 0x14a0
	v_mad_u32_u24 v51, v0, s3, v1
	v_mov_b32_e32 v1, 0x15a8
	v_mad_u32_u24 v52, v0, s3, v1
	v_mov_b32_e32 v1, 0x16b0
	s_mulk_i32 s2, 0x2100
	v_mad_u32_u24 v53, v0, s3, v1
	v_mov_b32_e32 v1, 0x17b8
	v_lshrrev_b32_e32 v55, 3, v34
	v_and_b32_e32 v6, 56, v66
	s_add_i32 s2, s2, 0
	v_mad_u32_u24 v54, v0, s3, v1
	v_mul_u32_u24_e32 v1, 0x84, v6
	v_lshlrev_b32_e32 v4, 2, v55
	s_waitcnt lgkmcnt(0)
	s_add_u32 s5, s20, 0x390800
	v_and_b32_e32 v2, 31, v64
	v_mov_b32_e32 v5, 0
	v_add3_u32 v56, s2, v1, v4
	v_mov_b32_e32 v1, 0x18c0
	s_mov_b32 s7, 0
	s_addc_u32 s15, s21, 0
	v_lshl_add_u32 v3, v2, 2, s2
	v_mul_u32_u24_e32 v7, 0x84, v0
	v_or_b32_e32 v12, 2, v0
	v_or_b32_e32 v14, 4, v0
	v_or_b32_e32 v16, 6, v0
	v_or_b32_e32 v18, 8, v0
	v_or_b32_e32 v20, 10, v0
	v_or_b32_e32 v22, 12, v0
	v_or_b32_e32 v24, 14, v0
	v_or_b32_e32 v26, 16, v0
	v_or_b32_e32 v28, 18, v0
	v_or_b32_e32 v30, 20, v0
	v_or_b32_e32 v32, 22, v0
	v_or_b32_e32 v35, 24, v0
	v_or_b32_e32 v37, 26, v0
	v_or_b32_e32 v39, 28, v0
	v_or_b32_e32 v41, 30, v0
	v_or_b32_e32 v43, 32, v0
	v_or_b32_e32 v45, 34, v0
	v_or_b32_e32 v47, 36, v0
	v_or_b32_e32 v49, 38, v0
	v_mad_u32_u24 v57, v0, s3, v1
	v_mov_b32_e32 v1, v5
	s_lshl_b32 s19, s4, 1
	s_lshl_b32 s40, s16, 4
	s_lshl_b32 s41, s4, 5
	s_lshl_b32 s42, s16, 8
	s_mov_b64 s[8:9], 0x1410000
	s_mov_b64 s[10:11], 0xc10000
	s_mov_b64 s[12:13], 0xa10000
	s_mov_b64 s[22:23], 0x810000
	s_movk_i32 s43, 0xf920
	s_movk_i32 s44, 0x300
	s_movk_i32 s45, 0xc00
	s_mov_b64 s[24:25], 0x680000
	s_mov_b32 s46, s4
	v_or_b32_e32 v58, 40, v0
	v_or_b32_e32 v59, 42, v0
	v_or_b32_e32 v60, 44, v0
	v_or_b32_e32 v61, 46, v0
	v_or_b32_e32 v62, 48, v0
	v_or_b32_e32 v63, 50, v0
	v_or_b32_e32 v67, 52, v0
	v_or_b32_e32 v68, 54, v0
	v_or_b32_e32 v69, 56, v0
	v_or_b32_e32 v70, 58, v0
	v_or_b32_e32 v71, 60, v0
	v_or_b32_e32 v72, 62, v0
	v_or_b32_e32 v73, 8, v55
	v_or_b32_e32 v74, 16, v55
	v_or_b32_e32 v75, 24, v55
	s_branch .LBB0_28

; #define LAS __attribute__((address_space(3)))
; #define TID() tid_now(wv)
; DEVI unsigned char* WSP() { return *(unsigned char* const __attribute__((address_space(4)))*)(kargs() + 8 * 22); }
; DEVI unsigned xb_add(unsigned* p, unsigned v) { return __hip_atomic_fetch_add(p, v, __ATOMIC_RELAXED, __HIP_MEMORY_SCOPE_AGENT); }
; DEVI unsigned xb_xcc_id() { return (unsigned)__builtin_amdgcn_s_getreg((3 << 11) | 20) & 0xFu; }
; #define WL(l, o) ((const bf16_t*)(WSP() + O_W + (size_t)(l) * W_LAYER + (o)))
; #define WSB(o) ((const bf16_t*)(WSP() + (o)))
; DEVI void grid_bar(int wv, LAS unsigned char* lds) {
;     asm volatile("s_waitcnt vmcnt(0)" ::: "memory");
;     __syncthreads();
;     if (TID() == 0) {
;         unsigned* bar = (unsigned*)(WSP() + O_CTL);
;         volatile LAS unsigned* st = (volatile LAS unsigned*)(lds + LDS_MISC);
;         const unsigned x = xb_xcc_id();
;         __builtin_amdgcn_s_waitcnt(0);
;         unsigned nloc = st[0], nx = st[1];
;         if (nloc == 0u) { xcd_barrier_complete(bar, x, nloc, nx); st[0] = nloc; st[1] = nx; }
;         const unsigned old = xb_add(&bar[XB_XSUB(x)], 1u);
;         const unsigned gen = old / nloc;
;         if (old + 1u == (gen + 1u) * nloc) {
; __global__ void __launch_bounds__(512, 2) fwd_kernel(Args args_unused) {
;     ...
;         { EpiZ E{l}; run_gemm(wv, lds, WSB(O_XB), WL(l, W_IN), 1024, 1024, MT, NZ, 1024, off, E); }
;         grid_bar(wv, lds);
.LBB0_715:
	s_waitcnt vmcnt(0) lgkmcnt(0)
	s_load_dword vcc_lo, s[0:1], 0xb8
	v_readlane_b32 vcc_hi, v255, 5
	s_waitcnt lgkmcnt(0)
	s_cmp_lg_u32 vcc_lo, 0x100
	s_cbranch_scc1 .Lsj_skip1
	s_sub_i32 vcc_hi, vcc_hi, 154
	s_and_b32 vcc_hi, vcc_hi, 0xff
	s_cmp_ge_u32 vcc_hi, 102
	s_cbranch_scc1 .Lsj_skip1
	v_readlane_b32 vcc_lo, v255, 0
	s_cmp_eq_u32 vcc_lo, 0
	s_cbranch_scc1 .Lsj_skip1
	v_writelane_b32 v201, s0, 0
	v_writelane_b32 v201, s1, 1
	v_writelane_b32 v201, s2, 2
	v_writelane_b32 v201, s3, 3
	v_writelane_b32 v201, s4, 4
	v_writelane_b32 v201, s5, 5
	v_writelane_b32 v201, s6, 6
	v_writelane_b32 v201, s7, 7
	v_writelane_b32 v201, s8, 8
	v_writelane_b32 v201, s9, 9
	v_writelane_b32 v201, s10, 10
	v_writelane_b32 v201, s11, 11
	v_writelane_b32 v201, s12, 12
	v_writelane_b32 v201, s13, 13
	v_writelane_b32 v201, s14, 14
	v_writelane_b32 v201, s15, 15
	v_writelane_b32 v201, s16, 16
	v_writelane_b32 v201, s17, 17
	v_writelane_b32 v201, s18, 18
	v_writelane_b32 v201, s19, 19
	v_writelane_b32 v201, s20, 20
	v_writelane_b32 v201, s21, 21
	v_writelane_b32 v201, s22, 22
	v_writelane_b32 v201, s23, 23
	v_writelane_b32 v201, s24, 24
	v_writelane_b32 v201, s25, 25
	v_writelane_b32 v201, s26, 26
	v_writelane_b32 v201, s27, 27
	v_writelane_b32 v201, s28, 28
	v_writelane_b32 v201, s29, 29
	v_writelane_b32 v201, s30, 30
	v_writelane_b32 v201, s31, 31
	v_writelane_b32 v201, s32, 32
	v_writelane_b32 v201, s33, 33
	v_writelane_b32 v201, s34, 34
	v_writelane_b32 v201, s35, 35
	v_writelane_b32 v201, s36, 36
	v_writelane_b32 v201, s37, 37
	v_writelane_b32 v201, s38, 38
	v_writelane_b32 v201, s39, 39
	v_writelane_b32 v201, s40, 40
	v_writelane_b32 v201, s41, 41
	v_writelane_b32 v201, s42, 42
	v_writelane_b32 v201, s43, 43
	v_writelane_b32 v201, s44, 44
	v_writelane_b32 v201, s45, 45
	v_writelane_b32 v201, s46, 46
	v_writelane_b32 v201, s47, 47
	v_writelane_b32 v201, s48, 48
	v_writelane_b32 v201, s49, 49
	v_writelane_b32 v201, s50, 50
	v_writelane_b32 v201, s51, 51
	v_writelane_b32 v201, s52, 52
	v_writelane_b32 v201, s53, 53
	v_writelane_b32 v201, s54, 54
	v_writelane_b32 v201, s55, 55
	v_writelane_b32 v201, s56, 56
	v_writelane_b32 v201, s57, 57
	v_writelane_b32 v201, s58, 58
	v_writelane_b32 v201, s59, 59
	v_writelane_b32 v201, s60, 60
	v_writelane_b32 v201, s61, 61
	v_writelane_b32 v201, s62, 62
	v_writelane_b32 v201, s63, 63
	v_writelane_b32 v202, s64, 0
	v_writelane_b32 v202, s65, 1
	v_writelane_b32 v202, s66, 2
	v_writelane_b32 v202, s67, 3
	v_writelane_b32 v202, s68, 4
	v_writelane_b32 v202, s69, 5
	v_writelane_b32 v202, s70, 6
	v_writelane_b32 v202, s71, 7
	v_writelane_b32 v202, s72, 8
	v_writelane_b32 v202, s73, 9
	v_writelane_b32 v202, s74, 10
	v_writelane_b32 v202, s75, 11
	v_writelane_b32 v202, s76, 12
	v_writelane_b32 v202, s77, 13
	v_writelane_b32 v202, s78, 14
	v_writelane_b32 v202, s79, 15
	v_writelane_b32 v202, s80, 16
	v_writelane_b32 v202, s81, 17
	v_writelane_b32 v202, s82, 18
	v_writelane_b32 v202, s83, 19
	v_writelane_b32 v202, s84, 20
	v_writelane_b32 v202, s85, 21
	v_writelane_b32 v202, s86, 22
	v_writelane_b32 v202, s87, 23
	v_writelane_b32 v202, s88, 24
	v_writelane_b32 v202, s89, 25
	v_writelane_b32 v202, s90, 26
	v_writelane_b32 v202, s91, 27
	v_writelane_b32 v202, s92, 28
	v_writelane_b32 v202, s93, 29
	v_writelane_b32 v202, s94, 30
	v_writelane_b32 v202, s95, 31
	v_writelane_b32 v202, s96, 32
	v_writelane_b32 v202, s97, 33
	v_writelane_b32 v202, s98, 34
	v_writelane_b32 v202, s99, 35
	v_mov_b32_e32 v200, v1
	s_mov_b32 s54, 0
	s_mov_b32 s52, -1
	s_cmp_lg_u32 vcc_lo, 0
	s_cbranch_scc0 .Lsj_par1
	s_mov_b32 s54, 2784
	s_mov_b32 s52, 3599
.Lsj_par1:
	s_mov_b32 s16, 102
	s_mov_b32 s18, vcc_hi
	s_mov_b32 s53, 1
	s_mov_b64 s[6:7], s[0:1]
	s_branch .Lsj_entry
.Lsj_ret1:
.Lsj_skip1:
	s_waitcnt vmcnt(0)
	s_waitcnt lgkmcnt(0)
	s_barrier
	v_mbcnt_lo_u32_b32 v0, -1, 0
	v_mbcnt_hi_u32_b32 v0, -1, v0
	v_lshl_or_b32 v0, s33, 6, v0
	s_nop 0
	v_cmp_eq_u32_e32 vcc, 0, v0
	s_and_saveexec_b64 s[2:3], vcc
	s_cbranch_execz .LBB0_767
	s_mov_b64 s[4:5], s[0:1]
	v_mov_b32_e32 v0, s80
	s_load_dwordx2 s[4:5], s[4:5], 0xb0
	s_getreg_b32 s6, hwreg(HW_REG_XCC_ID, 0, 4)
	s_waitcnt vmcnt(0) expcnt(0) lgkmcnt(0)
	ds_read_b32 v3, v0
	v_mov_b32_e32 v0, s81
	ds_read_b32 v0, v0
	s_and_b32 s12, s6, 15
	s_waitcnt lgkmcnt(1)
	v_cmp_ne_u32_e32 vcc, 0, v3
	s_cbranch_vccnz .LBB0_731
	s_add_u32 s6, s4, 0x1000
	s_addc_u32 s7, s5, 0
	s_add_u32 s8, s4, 0x1100
	s_addc_u32 s9, s5, 0
	s_add_u32 s10, s4, 0x1200
	s_addc_u32 s11, s5, 0
	s_add_u32 s48, s4, 0x1300
	s_addc_u32 s49, s5, 0
	s_mov_b32 s15, 1
	s_branch .LBB0_719

; DEVI const float* IN(int i) { return *(const float* const __attribute__((address_space(4)))*)(kargs() + 8 * i); }
; DEVI void prologue(int wv, LAS unsigned char* lds) {
;     ...
;     for (int it = gw; it < 2 * I_L; it += NGW) {
;         const int l = it / I_L; int r = it % I_L;
;         unsigned char* wl = ws + O_W + (size_t)l * W_LAYER;
;         if (r < I_IN) { const int kb = r / 101, nb = r % 101, n0 = nb * 32;
;             const int d0 = n0 < 384 ? n0 : n0 < 640 ? 512 + (n0 - 384) : n0 < 672 ? 384 + (n0 - 640) : n0 < 1184 ? 768 + (n0 - 672) : n0 < 2208 ? 1280 + (n0 - 1184) : 2304 + (n0 - 2208);
;             tr_item(IN(6) + (size_t)l * 1024 * 3232, 3232, 1024, IN(5) + l * 1024, (bf16_t*)(wl + W_IN), d0, scr, kb * 64, n0, lane); continue; }
;         r -= I_IN;
;         if (r < I_UQ) { const int kb = r / 24, nb = r % 24, n0 = nb * 32, hd = n0 / 96, dim0 = n0 % 96;
;             const int d0 = dim0 < 64 ? 256 * (hd >> 2) + 128 * (dim0 >> 5) + 32 * (hd & 3) : 512 + 128 * (hd >> 2) + 32 * (hd & 3);
;             tr_item(IN(9) + (size_t)l * 384 * 768, 768, 384, IN(7) + l * 384, (bf16_t*)(wl + W_UQ), d0, scr, kb * 64, n0, lane); continue; }
;         r -= I_UQ;
;         if (r < 2 * I_KV) { const int fold = r < I_KV; if (!fold) r -= I_KV;
;             const int kb = r / 32, nb = r % 32, n0 = nb * 32, hd = n0 / 128, dim0 = n0 % 128;
;             const bool isk = dim0 < 64;
;             const int d0 = isk ? 256 * (hd >> 2) + 128 * (dim0 >> 5) + 32 * (hd & 3) : hd * 64 + (dim0 - 64);
;             bf16_t* dst = (bf16_t*)(wl + (fold ? (isk ? W_K : W_V) : (isk ? W_KC : W_VC)));
;             tr_item(IN(10) + (size_t)l * 256 * 1024, 1024, 256, fold ? IN(8) + l * 256 : nullptr, dst, d0, scr, kb * 64, n0, lane); continue; }
;         r -= 2 * I_KV;
;         if (r < I_A) { tr_item(IN(13) + (size_t)l * 512 * 1024, 1024, 512, nullptr, (bf16_t*)(wl + W_A), (r % 32) * 32, scr, (r / 32) * 64, (r % 32) * 32, lane); continue; }
;         r -= I_A;
;         if (r < I_O) { tr_item(IN(17) + (size_t)l * 1024 * 1024, 1024, 1024, nullptr, (bf16_t*)(wl + W_O), (r % 32) * 32, scr, (r / 32) * 64, (r % 32) * 32, lane); continue; }
;         r -= I_O;
;         if (r < I_UP) { tr_item(IN(19) + (size_t)l * 1024 * 4096, 4096, 1024, IN(18) + l * 1024, (bf16_t*)(wl + W_UP), (r % 128) * 32, scr, (r / 128) * 64, (r % 128) * 32, lane); continue; }
;         r -= I_UP;
.LBB0_1230:
	s_waitcnt vmcnt(0) lgkmcnt(0)
	s_load_dword vcc_lo, s[0:1], 0xb8
	v_readlane_b32 vcc_hi, v255, 5
	s_waitcnt lgkmcnt(0)
	s_cmp_lg_u32 vcc_lo, 0x100
	s_cbranch_scc1 .Lsj_skip2
	s_sub_i32 vcc_hi, vcc_hi, 32
	s_and_b32 vcc_hi, vcc_hi, 0xff
	s_cmp_ge_u32 vcc_hi, 122
	s_cbranch_scc1 .Lsj_skip2
	v_readlane_b32 vcc_lo, v255, 0
	s_cmp_eq_u32 vcc_lo, 0
	s_cbranch_scc1 .Lsj_skip2
	v_writelane_b32 v201, s0, 0
	v_writelane_b32 v201, s1, 1
	v_writelane_b32 v201, s2, 2
	v_writelane_b32 v201, s3, 3
	v_writelane_b32 v201, s4, 4
	v_writelane_b32 v201, s5, 5
	v_writelane_b32 v201, s6, 6
	v_writelane_b32 v201, s7, 7
	v_writelane_b32 v201, s8, 8
	v_writelane_b32 v201, s9, 9
	v_writelane_b32 v201, s10, 10
	v_writelane_b32 v201, s11, 11
	v_writelane_b32 v201, s12, 12
	v_writelane_b32 v201, s13, 13
	v_writelane_b32 v201, s14, 14
	v_writelane_b32 v201, s15, 15
	v_writelane_b32 v201, s16, 16
	v_writelane_b32 v201, s17, 17
	v_writelane_b32 v201, s18, 18
	v_writelane_b32 v201, s19, 19
	v_writelane_b32 v201, s20, 20
	v_writelane_b32 v201, s21, 21
	v_writelane_b32 v201, s22, 22
	v_writelane_b32 v201, s23, 23
	v_writelane_b32 v201, s24, 24
	v_writelane_b32 v201, s25, 25
	v_writelane_b32 v201, s26, 26
	v_writelane_b32 v201, s27, 27
	v_writelane_b32 v201, s28, 28
	v_writelane_b32 v201, s29, 29
	v_writelane_b32 v201, s30, 30
	v_writelane_b32 v201, s31, 31
	v_writelane_b32 v201, s32, 32
	v_writelane_b32 v201, s33, 33
	v_writelane_b32 v201, s34, 34
	v_writelane_b32 v201, s35, 35
	v_writelane_b32 v201, s36, 36
	v_writelane_b32 v201, s37, 37
	v_writelane_b32 v201, s38, 38
	v_writelane_b32 v201, s39, 39
	v_writelane_b32 v201, s40, 40
	v_writelane_b32 v201, s41, 41
	v_writelane_b32 v201, s42, 42
	v_writelane_b32 v201, s43, 43
	v_writelane_b32 v201, s44, 44
	v_writelane_b32 v201, s45, 45
	v_writelane_b32 v201, s46, 46
	v_writelane_b32 v201, s47, 47
	v_writelane_b32 v201, s48, 48
	v_writelane_b32 v201, s49, 49
	v_writelane_b32 v201, s50, 50
	v_writelane_b32 v201, s51, 51
	v_writelane_b32 v201, s52, 52
	v_writelane_b32 v201, s53, 53
	v_writelane_b32 v201, s54, 54
	v_writelane_b32 v201, s55, 55
	v_writelane_b32 v201, s56, 56
	v_writelane_b32 v201, s57, 57
	v_writelane_b32 v201, s58, 58
	v_writelane_b32 v201, s59, 59
	v_writelane_b32 v201, s60, 60
	v_writelane_b32 v201, s61, 61
	v_writelane_b32 v201, s62, 62
	v_writelane_b32 v201, s63, 63
	v_writelane_b32 v202, s64, 0
	v_writelane_b32 v202, s65, 1
	v_writelane_b32 v202, s66, 2
	v_writelane_b32 v202, s67, 3
	v_writelane_b32 v202, s68, 4
	v_writelane_b32 v202, s69, 5
	v_writelane_b32 v202, s70, 6
	v_writelane_b32 v202, s71, 7
	v_writelane_b32 v202, s72, 8
	v_writelane_b32 v202, s73, 9
	v_writelane_b32 v202, s74, 10
	v_writelane_b32 v202, s75, 11
	v_writelane_b32 v202, s76, 12
	v_writelane_b32 v202, s77, 13
	v_writelane_b32 v202, s78, 14
	v_writelane_b32 v202, s79, 15
	v_writelane_b32 v202, s80, 16
	v_writelane_b32 v202, s81, 17
	v_writelane_b32 v202, s82, 18
	v_writelane_b32 v202, s83, 19
	v_writelane_b32 v202, s84, 20
	v_writelane_b32 v202, s85, 21
	v_writelane_b32 v202, s86, 22
	v_writelane_b32 v202, s87, 23
	v_writelane_b32 v202, s88, 24
	v_writelane_b32 v202, s89, 25
	v_writelane_b32 v202, s90, 26
	v_writelane_b32 v202, s91, 27
	v_writelane_b32 v202, s92, 28
	v_writelane_b32 v202, s93, 29
	v_writelane_b32 v202, s94, 30
	v_writelane_b32 v202, s95, 31
	v_writelane_b32 v202, s96, 32
	v_writelane_b32 v202, s97, 33
	v_writelane_b32 v202, s98, 34
	v_writelane_b32 v202, s99, 35
	v_mov_b32_e32 v200, v1
	s_mov_b32 s54, 0
	s_mov_b32 s52, -1
	s_cmp_lg_u32 vcc_lo, 0
	s_cbranch_scc0 .Lsj_par2
	s_mov_b32 s54, 3600
	s_mov_b32 s52, 4575
.Lsj_par2:
	s_mov_b32 s16, 122
	s_mov_b32 s18, vcc_hi
	s_mov_b32 s53, 2
	s_mov_b64 s[6:7], s[0:1]

; DEVI const float* IN(int i) { return *(const float* const __attribute__((address_space(4)))*)(kargs() + 8 * i); }
; DEVI void prologue(int wv, LAS unsigned char* lds) {
;     ...
;     for (int it = gw; it < 2 * I_L; it += NGW) {
;         const int l = it / I_L; int r = it % I_L;
;         unsigned char* wl = ws + O_W + (size_t)l * W_LAYER;
;         if (r < I_IN) { const int kb = r / 101, nb = r % 101, n0 = nb * 32;
;             const int d0 = n0 < 384 ? n0 : n0 < 640 ? 512 + (n0 - 384) : n0 < 672 ? 384 + (n0 - 640) : n0 < 1184 ? 768 + (n0 - 672) : n0 < 2208 ? 1280 + (n0 - 1184) : 2304 + (n0 - 2208);
;             tr_item(IN(6) + (size_t)l * 1024 * 3232, 3232, 1024, IN(5) + l * 1024, (bf16_t*)(wl + W_IN), d0, scr, kb * 64, n0, lane); continue; }
;         r -= I_IN;
;         if (r < I_UQ) { const int kb = r / 24, nb = r % 24, n0 = nb * 32, hd = n0 / 96, dim0 = n0 % 96;
;             const int d0 = dim0 < 64 ? 256 * (hd >> 2) + 128 * (dim0 >> 5) + 32 * (hd & 3) : 512 + 128 * (hd >> 2) + 32 * (hd & 3);
;             tr_item(IN(9) + (size_t)l * 384 * 768, 768, 384, IN(7) + l * 384, (bf16_t*)(wl + W_UQ), d0, scr, kb * 64, n0, lane); continue; }
;         r -= I_UQ;
;         if (r < 2 * I_KV) { const int fold = r < I_KV; if (!fold) r -= I_KV;
;             const int kb = r / 32, nb = r % 32, n0 = nb * 32, hd = n0 / 128, dim0 = n0 % 128;
;             const bool isk = dim0 < 64;
;             const int d0 = isk ? 256 * (hd >> 2) + 128 * (dim0 >> 5) + 32 * (hd & 3) : hd * 64 + (dim0 - 64);
;             bf16_t* dst = (bf16_t*)(wl + (fold ? (isk ? W_K : W_V) : (isk ? W_KC : W_VC)));
;             tr_item(IN(10) + (size_t)l * 256 * 1024, 1024, 256, fold ? IN(8) + l * 256 : nullptr, dst, d0, scr, kb * 64, n0, lane); continue; }
;         r -= 2 * I_KV;
;         if (r < I_A) { tr_item(IN(13) + (size_t)l * 512 * 1024, 1024, 512, nullptr, (bf16_t*)(wl + W_A), (r % 32) * 32, scr, (r / 32) * 64, (r % 32) * 32, lane); continue; }
;         r -= I_A;
;         if (r < I_O) { tr_item(IN(17) + (size_t)l * 1024 * 1024, 1024, 1024, nullptr, (bf16_t*)(wl + W_O), (r % 32) * 32, scr, (r / 32) * 64, (r % 32) * 32, lane); continue; }
;         r -= I_O;
;         if (r < I_UP) { tr_item(IN(19) + (size_t)l * 1024 * 4096, 4096, 1024, IN(18) + l * 1024, (bf16_t*)(wl + W_UP), (r % 128) * 32, scr, (r / 128) * 64, (r % 128) * 32, lane); continue; }
;         r -= I_UP;
.Lsj_end:
	s_mov_b64 exec, -1
	s_waitcnt lgkmcnt(0)
	s_mov_b32 vcc_lo, s53
	v_mov_b32_e32 v1, v200
	v_readlane_b32 s0, v201, 0
	v_readlane_b32 s1, v201, 1
	v_readlane_b32 s2, v201, 2
	v_readlane_b32 s3, v201, 3
	v_readlane_b32 s4, v201, 4
	v_readlane_b32 s5, v201, 5
	v_readlane_b32 s6, v201, 6
	v_readlane_b32 s7, v201, 7
	v_readlane_b32 s8, v201, 8
	v_readlane_b32 s9, v201, 9
	v_readlane_b32 s10, v201, 10
	v_readlane_b32 s11, v201, 11
	v_readlane_b32 s12, v201, 12
	v_readlane_b32 s13, v201, 13
	v_readlane_b32 s14, v201, 14
	v_readlane_b32 s15, v201, 15
	v_readlane_b32 s16, v201, 16
	v_readlane_b32 s17, v201, 17
	v_readlane_b32 s18, v201, 18
	v_readlane_b32 s19, v201, 19
	v_readlane_b32 s20, v201, 20
	v_readlane_b32 s21, v201, 21
	v_readlane_b32 s22, v201, 22
	v_readlane_b32 s23, v201, 23
	v_readlane_b32 s24, v201, 24
	v_readlane_b32 s25, v201, 25
	v_readlane_b32 s26, v201, 26
	v_readlane_b32 s27, v201, 27
	v_readlane_b32 s28, v201, 28
	v_readlane_b32 s29, v201, 29
	v_readlane_b32 s30, v201, 30
	v_readlane_b32 s31, v201, 31
	v_readlane_b32 s32, v201, 32
	v_readlane_b32 s33, v201, 33
	v_readlane_b32 s34, v201, 34
	v_readlane_b32 s35, v201, 35
	v_readlane_b32 s36, v201, 36
	v_readlane_b32 s37, v201, 37
	v_readlane_b32 s38, v201, 38
	v_readlane_b32 s39, v201, 39
	v_readlane_b32 s40, v201, 40
	v_readlane_b32 s41, v201, 41
	v_readlane_b32 s42, v201, 42
	v_readlane_b32 s43, v201, 43
	v_readlane_b32 s44, v201, 44
	v_readlane_b32 s45, v201, 45
	v_readlane_b32 s46, v201, 46
	v_readlane_b32 s47, v201, 47
	v_readlane_b32 s48, v201, 48
	v_readlane_b32 s49, v201, 49
	v_readlane_b32 s50, v201, 50
	v_readlane_b32 s51, v201, 51
	v_readlane_b32 s52, v201, 52
	v_readlane_b32 s53, v201, 53
	v_readlane_b32 s54, v201, 54
	v_readlane_b32 s55, v201, 55
	v_readlane_b32 s56, v201, 56
	v_readlane_b32 s57, v201, 57
	v_readlane_b32 s58, v201, 58
	v_readlane_b32 s59, v201, 59
	v_readlane_b32 s60, v201, 60
	v_readlane_b32 s61, v201, 61
	v_readlane_b32 s62, v201, 62
	v_readlane_b32 s63, v201, 63
	v_readlane_b32 s64, v202, 0
	v_readlane_b32 s65, v202, 1
	v_readlane_b32 s66, v202, 2
	v_readlane_b32 s67, v202, 3
	v_readlane_b32 s68, v202, 4
	v_readlane_b32 s69, v202, 5
	v_readlane_b32 s70, v202, 6
	v_readlane_b32 s71, v202, 7
	v_readlane_b32 s72, v202, 8
	v_readlane_b32 s73, v202, 9
	v_readlane_b32 s74, v202, 10
	v_readlane_b32 s75, v202, 11
	v_readlane_b32 s76, v202, 12
	v_readlane_b32 s77, v202, 13
	v_readlane_b32 s78, v202, 14
	v_readlane_b32 s79, v202, 15
	v_readlane_b32 s80, v202, 16
	v_readlane_b32 s81, v202, 17
	v_readlane_b32 s82, v202, 18
	v_readlane_b32 s83, v202, 19
	v_readlane_b32 s84, v202, 20
	v_readlane_b32 s85, v202, 21
	v_readlane_b32 s86, v202, 22
	v_readlane_b32 s87, v202, 23
	v_readlane_b32 s88, v202, 24
	v_readlane_b32 s89, v202, 25
	v_readlane_b32 s90, v202, 26
	v_readlane_b32 s91, v202, 27
	v_readlane_b32 s92, v202, 28
	v_readlane_b32 s93, v202, 29
	v_readlane_b32 s94, v202, 30
	v_readlane_b32 s95, v202, 31
	v_readlane_b32 s96, v202, 32
	v_readlane_b32 s97, v202, 33
	v_readlane_b32 s98, v202, 34
	v_readlane_b32 s99, v202, 35
	s_nop 7
	s_cmp_eq_u32 vcc_lo, 1
	s_cbranch_scc1 .Lsj_ret1
	s_cmp_eq_u32 vcc_lo, 4
	s_cbranch_scc1 .Lsj_ret4
	s_cmp_eq_u32 vcc_lo, 5
	s_cbranch_scc1 .Lsj_ret5
	s_cmp_eq_u32 vcc_lo, 6
	s_cbranch_scc1 .Lsj_ret6

; DEVI const float* IN(int i) { return *(const float* const __attribute__((address_space(4)))*)(kargs() + 8 * i); }
; DEVI void prologue(int wv, LAS unsigned char* lds) {
;     ...
;     for (int it = gw; it < 2 * I_L; it += NGW) {
;         const int l = it / I_L; int r = it % I_L;
;         unsigned char* wl = ws + O_W + (size_t)l * W_LAYER;
;         if (r < I_IN) { const int kb = r / 101, nb = r % 101, n0 = nb * 32;
;             const int d0 = n0 < 384 ? n0 : n0 < 640 ? 512 + (n0 - 384) : n0 < 672 ? 384 + (n0 - 640) : n0 < 1184 ? 768 + (n0 - 672) : n0 < 2208 ? 1280 + (n0 - 1184) : 2304 + (n0 - 2208);
;             tr_item(IN(6) + (size_t)l * 1024 * 3232, 3232, 1024, IN(5) + l * 1024, (bf16_t*)(wl + W_IN), d0, scr, kb * 64, n0, lane); continue; }
;         r -= I_IN;
;         if (r < I_UQ) { const int kb = r / 24, nb = r % 24, n0 = nb * 32, hd = n0 / 96, dim0 = n0 % 96;
;             const int d0 = dim0 < 64 ? 256 * (hd >> 2) + 128 * (dim0 >> 5) + 32 * (hd & 3) : 512 + 128 * (hd >> 2) + 32 * (hd & 3);
;             tr_item(IN(9) + (size_t)l * 384 * 768, 768, 384, IN(7) + l * 384, (bf16_t*)(wl + W_UQ), d0, scr, kb * 64, n0, lane); continue; }
;         r -= I_UQ;
;         if (r < 2 * I_KV) { const int fold = r < I_KV; if (!fold) r -= I_KV;
;             const int kb = r / 32, nb = r % 32, n0 = nb * 32, hd = n0 / 128, dim0 = n0 % 128;
;             const bool isk = dim0 < 64;
;             const int d0 = isk ? 256 * (hd >> 2) + 128 * (dim0 >> 5) + 32 * (hd & 3) : hd * 64 + (dim0 - 64);
;             bf16_t* dst = (bf16_t*)(wl + (fold ? (isk ? W_K : W_V) : (isk ? W_KC : W_VC)));
;             tr_item(IN(10) + (size_t)l * 256 * 1024, 1024, 256, fold ? IN(8) + l * 256 : nullptr, dst, d0, scr, kb * 64, n0, lane); continue; }
;         r -= 2 * I_KV;
;         if (r < I_A) { tr_item(IN(13) + (size_t)l * 512 * 1024, 1024, 512, nullptr, (bf16_t*)(wl + W_A), (r % 32) * 32, scr, (r / 32) * 64, (r % 32) * 32, lane); continue; }
;         r -= I_A;
;         if (r < I_O) { tr_item(IN(17) + (size_t)l * 1024 * 1024, 1024, 1024, nullptr, (bf16_t*)(wl + W_O), (r % 32) * 32, scr, (r / 32) * 64, (r % 32) * 32, lane); continue; }
;         r -= I_O;
;         if (r < I_UP) { tr_item(IN(19) + (size_t)l * 1024 * 4096, 4096, 1024, IN(18) + l * 1024, (bf16_t*)(wl + W_UP), (r % 128) * 32, scr, (r / 128) * 64, (r % 128) * 32, lane); continue; }
;         r -= I_UP;
.LBB0_1468:
	s_waitcnt vmcnt(0) lgkmcnt(0)
	s_load_dword vcc_lo, s[0:1], 0xb8
	v_readlane_b32 vcc_hi, v255, 5
	s_waitcnt lgkmcnt(0)
	s_cmp_lg_u32 vcc_lo, 0x100
	s_cbranch_scc1 .Lsj_skip4
	s_sub_i32 vcc_hi, vcc_hi, 48
	s_and_b32 vcc_hi, vcc_hi, 0xff
	s_cmp_ge_u32 vcc_hi, 248
	s_cbranch_scc1 .Lsj_skip4
	v_readlane_b32 vcc_lo, v255, 0
	v_writelane_b32 v201, s0, 0
	v_writelane_b32 v201, s1, 1
	v_writelane_b32 v201, s2, 2
	v_writelane_b32 v201, s3, 3
	v_writelane_b32 v201, s4, 4
	v_writelane_b32 v201, s5, 5
	v_writelane_b32 v201, s6, 6
	v_writelane_b32 v201, s7, 7
	v_writelane_b32 v201, s8, 8
	v_writelane_b32 v201, s9, 9
	v_writelane_b32 v201, s10, 10
	v_writelane_b32 v201, s11, 11
	v_writelane_b32 v201, s12, 12
	v_writelane_b32 v201, s13, 13
	v_writelane_b32 v201, s14, 14
	v_writelane_b32 v201, s15, 15
	v_writelane_b32 v201, s16, 16
	v_writelane_b32 v201, s17, 17
	v_writelane_b32 v201, s18, 18
	v_writelane_b32 v201, s19, 19
	v_writelane_b32 v201, s20, 20
	v_writelane_b32 v201, s21, 21
	v_writelane_b32 v201, s22, 22
	v_writelane_b32 v201, s23, 23
	v_writelane_b32 v201, s24, 24
	v_writelane_b32 v201, s25, 25
	v_writelane_b32 v201, s26, 26
	v_writelane_b32 v201, s27, 27
	v_writelane_b32 v201, s28, 28
	v_writelane_b32 v201, s29, 29
	v_writelane_b32 v201, s30, 30
	v_writelane_b32 v201, s31, 31
	v_writelane_b32 v201, s32, 32
	v_writelane_b32 v201, s33, 33
	v_writelane_b32 v201, s34, 34
	v_writelane_b32 v201, s35, 35
	v_writelane_b32 v201, s36, 36
	v_writelane_b32 v201, s37, 37
	v_writelane_b32 v201, s38, 38
	v_writelane_b32 v201, s39, 39
	v_writelane_b32 v201, s40, 40
	v_writelane_b32 v201, s41, 41
	v_writelane_b32 v201, s42, 42
	v_writelane_b32 v201, s43, 43
	v_writelane_b32 v201, s44, 44
	v_writelane_b32 v201, s45, 45
	v_writelane_b32 v201, s46, 46
	v_writelane_b32 v201, s47, 47
	v_writelane_b32 v201, s48, 48
	v_writelane_b32 v201, s49, 49
	v_writelane_b32 v201, s50, 50
	v_writelane_b32 v201, s51, 51
	v_writelane_b32 v201, s52, 52
	v_writelane_b32 v201, s53, 53
	v_writelane_b32 v201, s54, 54
	v_writelane_b32 v201, s55, 55
	v_writelane_b32 v201, s56, 56
	v_writelane_b32 v201, s57, 57
	v_writelane_b32 v201, s58, 58
	v_writelane_b32 v201, s59, 59
	v_writelane_b32 v201, s60, 60
	v_writelane_b32 v201, s61, 61
	v_writelane_b32 v201, s62, 62
	v_writelane_b32 v201, s63, 63
	v_writelane_b32 v202, s64, 0
	v_writelane_b32 v202, s65, 1
	v_writelane_b32 v202, s66, 2
	v_writelane_b32 v202, s67, 3
	v_writelane_b32 v202, s68, 4
	v_writelane_b32 v202, s69, 5
	v_writelane_b32 v202, s70, 6
	v_writelane_b32 v202, s71, 7
	v_writelane_b32 v202, s72, 8
	v_writelane_b32 v202, s73, 9
	v_writelane_b32 v202, s74, 10
	v_writelane_b32 v202, s75, 11
	v_writelane_b32 v202, s76, 12
	v_writelane_b32 v202, s77, 13
	v_writelane_b32 v202, s78, 14
	v_writelane_b32 v202, s79, 15
	v_writelane_b32 v202, s80, 16
	v_writelane_b32 v202, s81, 17
	v_writelane_b32 v202, s82, 18
	v_writelane_b32 v202, s83, 19
	v_writelane_b32 v202, s84, 20
	v_writelane_b32 v202, s85, 21
	v_writelane_b32 v202, s86, 22
	v_writelane_b32 v202, s87, 23
	v_writelane_b32 v202, s88, 24
	v_writelane_b32 v202, s89, 25
	v_writelane_b32 v202, s90, 26
	v_writelane_b32 v202, s91, 27
	v_writelane_b32 v202, s92, 28
	v_writelane_b32 v202, s93, 29
	v_writelane_b32 v202, s94, 30
	v_writelane_b32 v202, s95, 31
	v_writelane_b32 v202, s96, 32
	v_writelane_b32 v202, s97, 33
	v_writelane_b32 v202, s98, 34
	v_writelane_b32 v202, s99, 35
	v_mov_b32_e32 v200, v1
	s_mov_b32 s54, 12320
	s_mov_b32 s52, 13759
	s_cmp_lg_u32 vcc_lo, 0
	s_cbranch_scc0 .Lsj_par4
	s_mov_b32 s54, 4576
	s_mov_b32 s52, 6559

; DEVI const float* IN(int i) { return *(const float* const __attribute__((address_space(4)))*)(kargs() + 8 * i); }
; DEVI void prologue(int wv, LAS unsigned char* lds) {
;     ...
;     for (int it = gw; it < 2 * I_L; it += NGW) {
;         const int l = it / I_L; int r = it % I_L;
;         unsigned char* wl = ws + O_W + (size_t)l * W_LAYER;
;         if (r < I_IN) { const int kb = r / 101, nb = r % 101, n0 = nb * 32;
;             const int d0 = n0 < 384 ? n0 : n0 < 640 ? 512 + (n0 - 384) : n0 < 672 ? 384 + (n0 - 640) : n0 < 1184 ? 768 + (n0 - 672) : n0 < 2208 ? 1280 + (n0 - 1184) : 2304 + (n0 - 2208);
;             tr_item(IN(6) + (size_t)l * 1024 * 3232, 3232, 1024, IN(5) + l * 1024, (bf16_t*)(wl + W_IN), d0, scr, kb * 64, n0, lane); continue; }
;         r -= I_IN;
;         if (r < I_UQ) { const int kb = r / 24, nb = r % 24, n0 = nb * 32, hd = n0 / 96, dim0 = n0 % 96;
;             const int d0 = dim0 < 64 ? 256 * (hd >> 2) + 128 * (dim0 >> 5) + 32 * (hd & 3) : 512 + 128 * (hd >> 2) + 32 * (hd & 3);
;             tr_item(IN(9) + (size_t)l * 384 * 768, 768, 384, IN(7) + l * 384, (bf16_t*)(wl + W_UQ), d0, scr, kb * 64, n0, lane); continue; }
;         r -= I_UQ;
;         if (r < 2 * I_KV) { const int fold = r < I_KV; if (!fold) r -= I_KV;
;             const int kb = r / 32, nb = r % 32, n0 = nb * 32, hd = n0 / 128, dim0 = n0 % 128;
;             const bool isk = dim0 < 64;
;             const int d0 = isk ? 256 * (hd >> 2) + 128 * (dim0 >> 5) + 32 * (hd & 3) : hd * 64 + (dim0 - 64);
;             bf16_t* dst = (bf16_t*)(wl + (fold ? (isk ? W_K : W_V) : (isk ? W_KC : W_VC)));
;             tr_item(IN(10) + (size_t)l * 256 * 1024, 1024, 256, fold ? IN(8) + l * 256 : nullptr, dst, d0, scr, kb * 64, n0, lane); continue; }
;         r -= 2 * I_KV;
;         if (r < I_A) { tr_item(IN(13) + (size_t)l * 512 * 1024, 1024, 512, nullptr, (bf16_t*)(wl + W_A), (r % 32) * 32, scr, (r / 32) * 64, (r % 32) * 32, lane); continue; }
;         r -= I_A;
;         if (r < I_O) { tr_item(IN(17) + (size_t)l * 1024 * 1024, 1024, 1024, nullptr, (bf16_t*)(wl + W_O), (r % 32) * 32, scr, (r / 32) * 64, (r % 32) * 32, lane); continue; }
;         r -= I_O;
;         if (r < I_UP) { tr_item(IN(19) + (size_t)l * 1024 * 4096, 4096, 1024, IN(18) + l * 1024, (bf16_t*)(wl + W_UP), (r % 128) * 32, scr, (r / 128) * 64, (r % 128) * 32, lane); continue; }
;         r -= I_UP;
.LBB0_1559:
	s_waitcnt vmcnt(0) lgkmcnt(0)
	s_load_dword vcc_lo, s[0:1], 0xb8
	v_readlane_b32 vcc_hi, v255, 5
	s_waitcnt lgkmcnt(0)
	s_cmp_lg_u32 vcc_lo, 0x100
	s_cbranch_scc1 .Lsj_skip5
	s_sub_i32 vcc_hi, vcc_hi, 56
	s_and_b32 vcc_hi, vcc_hi, 0xff
	s_cmp_ge_u32 vcc_hi, 248
	s_cbranch_scc1 .Lsj_skip5
	v_readlane_b32 vcc_lo, v255, 0
	s_cmp_eq_u32 vcc_lo, 0
	s_cbranch_scc1 .Lsj_skip5
	v_writelane_b32 v201, s0, 0
	v_writelane_b32 v201, s1, 1
	v_writelane_b32 v201, s2, 2
	v_writelane_b32 v201, s3, 3
	v_writelane_b32 v201, s4, 4
	v_writelane_b32 v201, s5, 5
	v_writelane_b32 v201, s6, 6
	v_writelane_b32 v201, s7, 7
	v_writelane_b32 v201, s8, 8
	v_writelane_b32 v201, s9, 9
	v_writelane_b32 v201, s10, 10
	v_writelane_b32 v201, s11, 11
	v_writelane_b32 v201, s12, 12
	v_writelane_b32 v201, s13, 13
	v_writelane_b32 v201, s14, 14
	v_writelane_b32 v201, s15, 15
	v_writelane_b32 v201, s16, 16
	v_writelane_b32 v201, s17, 17
	v_writelane_b32 v201, s18, 18
	v_writelane_b32 v201, s19, 19
	v_writelane_b32 v201, s20, 20
	v_writelane_b32 v201, s21, 21
	v_writelane_b32 v201, s22, 22
	v_writelane_b32 v201, s23, 23
	v_writelane_b32 v201, s24, 24
	v_writelane_b32 v201, s25, 25
	v_writelane_b32 v201, s26, 26
	v_writelane_b32 v201, s27, 27
	v_writelane_b32 v201, s28, 28
	v_writelane_b32 v201, s29, 29
	v_writelane_b32 v201, s30, 30
	v_writelane_b32 v201, s31, 31
	v_writelane_b32 v201, s32, 32
	v_writelane_b32 v201, s33, 33
	v_writelane_b32 v201, s34, 34
	v_writelane_b32 v201, s35, 35
	v_writelane_b32 v201, s36, 36
	v_writelane_b32 v201, s37, 37
	v_writelane_b32 v201, s38, 38
	v_writelane_b32 v201, s39, 39
	v_writelane_b32 v201, s40, 40
	v_writelane_b32 v201, s41, 41
	v_writelane_b32 v201, s42, 42
	v_writelane_b32 v201, s43, 43
	v_writelane_b32 v201, s44, 44
	v_writelane_b32 v201, s45, 45
	v_writelane_b32 v201, s46, 46
	v_writelane_b32 v201, s47, 47
	v_writelane_b32 v201, s48, 48
	v_writelane_b32 v201, s49, 49
	v_writelane_b32 v201, s50, 50
	v_writelane_b32 v201, s51, 51
	v_writelane_b32 v201, s52, 52
	v_writelane_b32 v201, s53, 53
	v_writelane_b32 v201, s54, 54
	v_writelane_b32 v201, s55, 55
	v_writelane_b32 v201, s56, 56
	v_writelane_b32 v201, s57, 57
	v_writelane_b32 v201, s58, 58
	v_writelane_b32 v201, s59, 59
	v_writelane_b32 v201, s60, 60
	v_writelane_b32 v201, s61, 61
	v_writelane_b32 v201, s62, 62
	v_writelane_b32 v201, s63, 63
	v_writelane_b32 v202, s64, 0
	v_writelane_b32 v202, s65, 1
	v_writelane_b32 v202, s66, 2
	v_writelane_b32 v202, s67, 3
	v_writelane_b32 v202, s68, 4
	v_writelane_b32 v202, s69, 5
	v_writelane_b32 v202, s70, 6
	v_writelane_b32 v202, s71, 7
	v_writelane_b32 v202, s72, 8
	v_writelane_b32 v202, s73, 9
	v_writelane_b32 v202, s74, 10
	v_writelane_b32 v202, s75, 11
	v_writelane_b32 v202, s76, 12
	v_writelane_b32 v202, s77, 13
	v_writelane_b32 v202, s78, 14
	v_writelane_b32 v202, s79, 15
	v_writelane_b32 v202, s80, 16
	v_writelane_b32 v202, s81, 17
	v_writelane_b32 v202, s82, 18
	v_writelane_b32 v202, s83, 19
	v_writelane_b32 v202, s84, 20
	v_writelane_b32 v202, s85, 21
	v_writelane_b32 v202, s86, 22
	v_writelane_b32 v202, s87, 23
	v_writelane_b32 v202, s88, 24
	v_writelane_b32 v202, s89, 25
	v_writelane_b32 v202, s90, 26
	v_writelane_b32 v202, s91, 27
	v_writelane_b32 v202, s92, 28
	v_writelane_b32 v202, s93, 29
	v_writelane_b32 v202, s94, 30
	v_writelane_b32 v202, s95, 31
	v_writelane_b32 v202, s96, 32
	v_writelane_b32 v202, s97, 33
	v_writelane_b32 v202, s98, 34
	v_writelane_b32 v202, s99, 35
	v_mov_b32_e32 v200, v1
	s_mov_b32 s54, 0
	s_mov_b32 s52, -1
	s_cmp_lg_u32 vcc_lo, 0
	s_cbranch_scc0 .Lsj_par5
	s_mov_b32 s54, 6560
	s_mov_b32 s52, 10527
.Lsj_par5:
	s_mov_b32 s16, 248
	s_mov_b32 s18, vcc_hi
	s_mov_b32 s53, 5
	s_mov_b64 s[6:7], s[0:1]
	s_branch .Lsj_entry
.Lsj_ret5:
.Lsj_skip5:
	s_waitcnt vmcnt(0)
	s_waitcnt lgkmcnt(0)
	s_barrier
	v_mbcnt_lo_u32_b32 v0, -1, 0
	v_mbcnt_hi_u32_b32 v0, -1, v0
	v_lshl_or_b32 v0, s33, 6, v0
	s_nop 0
	v_cmp_eq_u32_e32 vcc, 0, v0
	s_and_saveexec_b64 s[2:3], vcc
	s_cbranch_execz .LBB0_1611
	s_mov_b64 s[4:5], s[0:1]
	v_mov_b32_e32 v0, s80
	s_load_dwordx2 s[4:5], s[4:5], 0xb0
	s_getreg_b32 s6, hwreg(HW_REG_XCC_ID, 0, 4)
	s_waitcnt vmcnt(0) expcnt(0) lgkmcnt(0)
	ds_read_b32 v3, v0
	v_mov_b32_e32 v0, s81
	ds_read_b32 v0, v0
	s_and_b32 s15, s6, 15
	s_waitcnt lgkmcnt(1)
	v_cmp_ne_u32_e32 vcc, 0, v3
	s_cbranch_vccnz .LBB0_1575
	s_add_u32 s6, s4, 0x1000
	s_addc_u32 s7, s5, 0
	s_add_u32 s8, s4, 0x1100
	s_addc_u32 s9, s5, 0
	s_add_u32 s10, s4, 0x1200
	s_addc_u32 s11, s5, 0
	s_add_u32 s46, s4, 0x1300
	s_addc_u32 s47, s5, 0
	s_mov_b32 s26, 1
	s_branch .LBB0_1563

; DEVI const float* IN(int i) { return *(const float* const __attribute__((address_space(4)))*)(kargs() + 8 * i); }
; DEVI void prologue(int wv, LAS unsigned char* lds) {
;     ...
;     for (int it = gw; it < 2 * I_L; it += NGW) {
;         const int l = it / I_L; int r = it % I_L;
;         unsigned char* wl = ws + O_W + (size_t)l * W_LAYER;
;         if (r < I_IN) { const int kb = r / 101, nb = r % 101, n0 = nb * 32;
;             const int d0 = n0 < 384 ? n0 : n0 < 640 ? 512 + (n0 - 384) : n0 < 672 ? 384 + (n0 - 640) : n0 < 1184 ? 768 + (n0 - 672) : n0 < 2208 ? 1280 + (n0 - 1184) : 2304 + (n0 - 2208);
;             tr_item(IN(6) + (size_t)l * 1024 * 3232, 3232, 1024, IN(5) + l * 1024, (bf16_t*)(wl + W_IN), d0, scr, kb * 64, n0, lane); continue; }
;         r -= I_IN;
;         if (r < I_UQ) { const int kb = r / 24, nb = r % 24, n0 = nb * 32, hd = n0 / 96, dim0 = n0 % 96;
;             const int d0 = dim0 < 64 ? 256 * (hd >> 2) + 128 * (dim0 >> 5) + 32 * (hd & 3) : 512 + 128 * (hd >> 2) + 32 * (hd & 3);
;             tr_item(IN(9) + (size_t)l * 384 * 768, 768, 384, IN(7) + l * 384, (bf16_t*)(wl + W_UQ), d0, scr, kb * 64, n0, lane); continue; }
;         r -= I_UQ;
;         if (r < 2 * I_KV) { const int fold = r < I_KV; if (!fold) r -= I_KV;
;             const int kb = r / 32, nb = r % 32, n0 = nb * 32, hd = n0 / 128, dim0 = n0 % 128;
;             const bool isk = dim0 < 64;
;             const int d0 = isk ? 256 * (hd >> 2) + 128 * (dim0 >> 5) + 32 * (hd & 3) : hd * 64 + (dim0 - 64);
;             bf16_t* dst = (bf16_t*)(wl + (fold ? (isk ? W_K : W_V) : (isk ? W_KC : W_VC)));
;             tr_item(IN(10) + (size_t)l * 256 * 1024, 1024, 256, fold ? IN(8) + l * 256 : nullptr, dst, d0, scr, kb * 64, n0, lane); continue; }
;         r -= 2 * I_KV;
;         if (r < I_A) { tr_item(IN(13) + (size_t)l * 512 * 1024, 1024, 512, nullptr, (bf16_t*)(wl + W_A), (r % 32) * 32, scr, (r / 32) * 64, (r % 32) * 32, lane); continue; }
;         r -= I_A;
;         if (r < I_O) { tr_item(IN(17) + (size_t)l * 1024 * 1024, 1024, 1024, nullptr, (bf16_t*)(wl + W_O), (r % 32) * 32, scr, (r / 32) * 64, (r % 32) * 32, lane); continue; }
;         r -= I_O;
;         if (r < I_UP) { tr_item(IN(19) + (size_t)l * 1024 * 4096, 4096, 1024, IN(18) + l * 1024, (bf16_t*)(wl + W_UP), (r % 128) * 32, scr, (r / 128) * 64, (r % 128) * 32, lane); continue; }
;         r -= I_UP;
.LBB0_1627:
	s_waitcnt vmcnt(0) lgkmcnt(0)
	s_load_dword vcc_lo, s[0:1], 0xb8
	v_readlane_b32 vcc_hi, v255, 5
	s_waitcnt lgkmcnt(0)
	s_cmp_lg_u32 vcc_lo, 0x100
	s_cbranch_scc1 .Lsj_skip6
	s_sub_i32 vcc_hi, vcc_hi, 88
	s_and_b32 vcc_hi, vcc_hi, 0xff
	s_cmp_ge_u32 vcc_hi, 224
	s_cbranch_scc1 .Lsj_skip6
	v_readlane_b32 vcc_lo, v255, 0
	s_cmp_eq_u32 vcc_lo, 0
	s_cbranch_scc1 .Lsj_skip6
	v_writelane_b32 v201, s0, 0
	v_writelane_b32 v201, s1, 1
	v_writelane_b32 v201, s2, 2
	v_writelane_b32 v201, s3, 3
	v_writelane_b32 v201, s4, 4
	v_writelane_b32 v201, s5, 5
	v_writelane_b32 v201, s6, 6
	v_writelane_b32 v201, s7, 7
	v_writelane_b32 v201, s8, 8
	v_writelane_b32 v201, s9, 9
	v_writelane_b32 v201, s10, 10
	v_writelane_b32 v201, s11, 11
	v_writelane_b32 v201, s12, 12
	v_writelane_b32 v201, s13, 13
	v_writelane_b32 v201, s14, 14
	v_writelane_b32 v201, s15, 15
	v_writelane_b32 v201, s16, 16
	v_writelane_b32 v201, s17, 17
	v_writelane_b32 v201, s18, 18
	v_writelane_b32 v201, s19, 19
	v_writelane_b32 v201, s20, 20
	v_writelane_b32 v201, s21, 21
	v_writelane_b32 v201, s22, 22
	v_writelane_b32 v201, s23, 23
	v_writelane_b32 v201, s24, 24
	v_writelane_b32 v201, s25, 25
	v_writelane_b32 v201, s26, 26
	v_writelane_b32 v201, s27, 27
	v_writelane_b32 v201, s28, 28
	v_writelane_b32 v201, s29, 29
	v_writelane_b32 v201, s30, 30
	v_writelane_b32 v201, s31, 31
	v_writelane_b32 v201, s32, 32
	v_writelane_b32 v201, s33, 33
	v_writelane_b32 v201, s34, 34
	v_writelane_b32 v201, s35, 35
	v_writelane_b32 v201, s36, 36
	v_writelane_b32 v201, s37, 37
	v_writelane_b32 v201, s38, 38
	v_writelane_b32 v201, s39, 39
	v_writelane_b32 v201, s40, 40
	v_writelane_b32 v201, s41, 41
	v_writelane_b32 v201, s42, 42
	v_writelane_b32 v201, s43, 43
	v_writelane_b32 v201, s44, 44
	v_writelane_b32 v201, s45, 45
	v_writelane_b32 v201, s46, 46
	v_writelane_b32 v201, s47, 47
	v_writelane_b32 v201, s48, 48
	v_writelane_b32 v201, s49, 49
	v_writelane_b32 v201, s50, 50
	v_writelane_b32 v201, s51, 51
	v_writelane_b32 v201, s52, 52
	v_writelane_b32 v201, s53, 53
	v_writelane_b32 v201, s54, 54
	v_writelane_b32 v201, s55, 55
	v_writelane_b32 v201, s56, 56
	v_writelane_b32 v201, s57, 57
	v_writelane_b32 v201, s58, 58
	v_writelane_b32 v201, s59, 59
	v_writelane_b32 v201, s60, 60
	v_writelane_b32 v201, s61, 61
	v_writelane_b32 v201, s62, 62
	v_writelane_b32 v201, s63, 63
	v_writelane_b32 v202, s64, 0
	v_writelane_b32 v202, s65, 1
	v_writelane_b32 v202, s66, 2
	v_writelane_b32 v202, s67, 3
	v_writelane_b32 v202, s68, 4
	v_writelane_b32 v202, s69, 5
	v_writelane_b32 v202, s70, 6
	v_writelane_b32 v202, s71, 7
	v_writelane_b32 v202, s72, 8
	v_writelane_b32 v202, s73, 9
	v_writelane_b32 v202, s74, 10
	v_writelane_b32 v202, s75, 11
	v_writelane_b32 v202, s76, 12
	v_writelane_b32 v202, s77, 13
	v_writelane_b32 v202, s78, 14
	v_writelane_b32 v202, s79, 15
	v_writelane_b32 v202, s80, 16
	v_writelane_b32 v202, s81, 17
	v_writelane_b32 v202, s82, 18
	v_writelane_b32 v202, s83, 19
	v_writelane_b32 v202, s84, 20
	v_writelane_b32 v202, s85, 21
	v_writelane_b32 v202, s86, 22
	v_writelane_b32 v202, s87, 23
	v_writelane_b32 v202, s88, 24
	v_writelane_b32 v202, s89, 25
	v_writelane_b32 v202, s90, 26
	v_writelane_b32 v202, s91, 27
	v_writelane_b32 v202, s92, 28
	v_writelane_b32 v202, s93, 29
	v_writelane_b32 v202, s94, 30
	v_writelane_b32 v202, s95, 31
	v_writelane_b32 v202, s96, 32
	v_writelane_b32 v202, s97, 33
	v_writelane_b32 v202, s98, 34
	v_writelane_b32 v202, s99, 35
	v_mov_b32_e32 v200, v1
	s_mov_b32 s54, 0
	s_mov_b32 s52, -1
	s_cmp_lg_u32 vcc_lo, 0
	s_cbranch_scc0 .Lsj_par6
	s_mov_b32 s54, 10528
	s_mov_b32 s52, 12319
